# v44 plus one static s_setprio 1 for the scan compute waves over their chunk loop
# baseline (speedup 1.0000x reference)
; #define LAS __attribute__((address_space(3)))
; __device__ __forceinline__ void s7_ops_load(S7Ops& o, const LAS float* vec, int n, int q, int i0) {
; #pragma unroll
;     for (int jt = 0; jt < 4; ++jt) { o.av[jt] = *(const LAS f32x4*)(vec + n * S7_STEP_F + 16 * jt + 4 * q); o.rv[jt] = *(const LAS f32x4*)(vec + n * S7_STEP_F + 4 * 64 + 16 * jt + 4 * q); }
; #pragma unroll
;     for (int kk = 0; kk < 4; ++kk) { o.vq[kk] = vec[(4 * q + kk) * S7_STEP_F + 5 * 64 + i0 + n];
; #pragma unroll
;         for (int jt = 0; jt < 4; ++jt) { o.bval[kk][jt] = vec[(4 * q + kk) * S7_STEP_F + 2 * 64 + 16 * jt + n]; o.kval[kk][jt] = vec[(4 * q + kk) * S7_STEP_F + 3 * 64 + 16 * jt + n]; } }
; }
; __device__ __forceinline__ void wkv_scan_mfma(const PT& a, int seq, LAS unsigned char* lds, unsigned long long& busy) {
;     ...
;     } else {
;         __syncthreads(); __syncthreads();
;         const int i0 = 16 * wave;
;         f32x4 St[4];
; #pragma unroll
;         for (int jt = 0; jt < 4; ++jt) St[jt] = (f32x4){0.f, 0.f, 0.f, 0.f};
;         S7Ops oA, oB;
;         s7_ops_load(oA, vec0, n, q, i0);
.LBB0_1204:
	s_and_b64 vcc, exec, s[0:1]
	s_cbranch_vccz .LBB0_1377
	v_mov_b32_e32 v1, 0x23a60
	v_mov_b32_e32 v232, v0
	v_add_u32_e32 v1, 0, v1
	ds_read_b64 v[2:3], v1
	s_waitcnt vmcnt(0) lgkmcnt(0)
	v_readfirstlane_b32 s0, v232
	s_ashr_i32 s14, s0, 6
	v_and_b32_e32 v230, 15, v232
	v_and_b32_e32 v231, 63, v232
	v_readfirstlane_b32 s2, v3
	v_readfirstlane_b32 s3, v2
	s_mov_b64 s[0:1], -1
	s_cmp_lt_i32 s14, 4
	v_lshlrev_b32_e32 v144, 2, v230
	v_lshlrev_b32_e32 v1, 6, v230
	s_barrier
	s_cbranch_scc0 .LBB0_1215
	v_lshrrev_b32_e32 v34, 4, v231
	v_readlane_b32 s0, v253, 51
	v_mul_u32_u24_e32 v235, 0x1840, v34
	v_readlane_b32 s1, v253, 52
	s_add_u32 s4, s3, s0
	v_mul_u32_u24_e32 v233, 0x610, v230
	v_lshlrev_b32_e32 v234, 2, v34
	v_and_b32_e32 v36, 48, v231
	v_add3_u32 v34, 0, v235, v144
	s_addc_u32 s5, s2, s1
	v_add3_u32 v30, 0, v233, v36
	v_add_u32_e32 v37, 0x800, v34
	v_readlane_b32 s1, v254, 34
	s_barrier
	s_barrier
	ds_read_b128 v[2:5], v30
	ds_read_b128 v[6:9], v30 offset:64
	ds_read_b128 v[10:13], v30 offset:1024
	ds_read_b128 v[14:17], v30 offset:1088
	ds_read_b128 v[18:21], v30 offset:128
	ds_read_b128 v[22:25], v30 offset:192
	ds_read_b128 v[26:29], v30 offset:1152
	ds_read_b128 v[30:33], v30 offset:1216
	ds_read2_b32 v[146:147], v34 offset0:128 offset1:144
	ds_read2_b32 v[148:149], v34 offset0:192 offset1:208
	ds_read2_b32 v[150:151], v34 offset0:160 offset1:176
	ds_read2_b32 v[152:153], v34 offset0:224 offset1:240
	ds_read2_b32 v[154:155], v37 offset0:4 offset1:20
	ds_read2_b32 v[156:157], v37 offset0:68 offset1:84
	ds_read2_b32 v[158:159], v37 offset0:36 offset1:52
	ds_read2_b32 v[160:161], v37 offset0:100 offset1:116
	v_add_u32_e32 v37, 0xc00, v34
	v_add3_u32 v236, s1, v1, v36
	v_readlane_b32 s1, v254, 35
	v_lshl_add_u32 v35, s14, 6, v34
	ds_read2_b32 v[164:165], v37 offset0:136 offset1:152
	ds_read2_b32 v[166:167], v37 offset0:200 offset1:216
	ds_read2_b32 v[168:169], v37 offset0:168 offset1:184
	ds_read2_b32 v[170:171], v37 offset0:232 offset1:248
	ds_read_b32 v246, v35 offset:1280
	ds_read_b32 v247, v35 offset:2832
	ds_read_b32 v248, v35 offset:4384
	ds_read_b32 v249, v35 offset:5936
	v_add3_u32 v237, s1, v1, v36
	v_readlane_b32 s1, v254, 36
	s_lshl_b32 s0, s14, 4
	v_readlane_b32 s6, v253, 47
	v_add3_u32 v238, s1, v1, v36
	v_readlane_b32 s1, v254, 37
	s_lshl_b32 s6, s6, 2
	v_add_u32_e32 v34, 0x1400, v34
	v_add3_u32 v239, s1, v1, v36
	s_ashr_i32 s1, s0, 31
	s_add_u32 s6, s4, s6
	ds_read2_b32 v[172:173], v34 offset0:12 offset1:28
	ds_read2_b32 v[174:175], v34 offset0:76 offset1:92
	ds_read2_b32 v[176:177], v34 offset0:44 offset1:60
	ds_read2_b32 v[178:179], v34 offset0:108 offset1:124
	s_addc_u32 s7, s5, 0
	s_lshl_b64 s[4:5], s[0:1], 2
	s_add_u32 s4, s6, s4
	s_addc_u32 s5, s7, s5
	v_mov_b32_e32 v145, v133
	v_readlane_b32 s1, v254, 38
	v_lshl_add_u64 v[34:35], s[4:5], 0, v[144:145]
	v_and_b32_e32 v37, 48, v232
	v_add3_u32 v145, s1, v1, v36
	v_readlane_b32 s1, v254, 39
	s_mov_b64 s[4:5], 0x56d00000
	v_mov_b32_e32 v82, 0
	v_add3_u32 v240, s1, v1, v36
	v_readlane_b32 s1, v254, 40
	v_readlane_b32 s8, v253, 53
	v_lshl_add_u64 v[162:163], v[34:35], 0, s[4:5]
	v_add3_u32 v241, s1, v1, v36
	v_readlane_b32 s1, v254, 41
	v_add_u32_e32 v243, 0, v37
	v_xor_b32_e32 v244, 0x7ff, v234
	v_add3_u32 v242, s1, v1, v36
	s_mov_b32 s1, 0
	v_mov_b32_e32 v245, v234
	v_mov_b32_e32 v83, v82
	v_mov_b32_e32 v84, v82
	v_mov_b32_e32 v85, v82
	v_mov_b32_e32 v86, v82
	v_mov_b32_e32 v87, v82
	v_mov_b32_e32 v88, v82
	v_mov_b32_e32 v89, v82
	v_mov_b32_e32 v90, v82
	v_mov_b32_e32 v91, v82
	v_mov_b32_e32 v92, v82
	v_mov_b32_e32 v93, v82
	v_mov_b32_e32 v94, v82
	v_mov_b32_e32 v95, v82
	v_mov_b32_e32 v96, v82
	v_mov_b32_e32 v97, v82
	v_readlane_b32 s6, v253, 48
	v_readlane_b32 s9, v253, 54
	s_setprio 1
	s_branch .LBB0_1212

; __device__ __forceinline__ void wkv_scan_mfma(const PT& a, int seq, LAS unsigned char* lds, unsigned long long& busy) {
;     ...
; #pragma unroll 1
;         for (int c = 0; c < NCH; c += 2) { S7_CITER(c, oA, oB); S7_CITER(c + 1, oB, oA); }
;     ...
;     }
.LBB0_1214:
	s_setprio 0
	s_mov_b64 s[0:1], 0
